# v18 + InN GEMM: per-tile vmcnt(0) drain in tile header moved to the one-time loop entry (as in the other 4 GEMMs)
# speedup vs baseline: 1.0009x; 1.0004x over previous
; #define PG8_STAGE(bufoff, gbase, voff) do { _Pragma("unroll") for (int _i = 0; _i < 2; ++_i) \
;         __builtin_amdgcn_global_load_lds((const unsigned*)((const char*)(gbase) + (voff)[_i]), (LAS unsigned*)(lds + (bufoff) + ldsw + _i * 8192), 16, 0, 0); } while (0)
; #define PG8_WAIT_V(n) asm volatile("s_waitcnt vmcnt(" #n ")" ::: "memory")
; #define PG8_BAR __builtin_amdgcn_s_barrier()
; template <class Epi>
; DI void gemm_phase(LAS unsigned char* lds, const Gemm g, const StaticOrder& S, const Epi& E, const int tid) {
;     const int wid = __builtin_amdgcn_readfirstlane(tid >> 6), lane = tid & 63, wr = wid >> 2, wc = wid & 3, fr = lane & 15, fq = lane >> 4;
;     const int K = g.K, nt = K / BK;
;     unsigned voffA[2], voffB[2];
; #pragma unroll
;     for (int i = 0; i < 2; ++i) { int R, C; stage_rc(tid * 16 + i * 8192, R, C); const int Rb = Epi::PERM ? ((R & ~31) + perm32(R & 31)) : R;
;         voffA[i] = (unsigned)(R * K + C) * 2u; voffB[i] = (unsigned)(Rb * K + C) * 2u; }
;     const size_t kstep = (size_t)(BK * 2);
;     const size_t hstep = (size_t)HALF * K * 2;
;     const size_t tstep = 2 * hstep;
;     const unsigned ldsw = (unsigned)wid * 1024u;
;     const int aoff = lds_byte(wr * 64 + fr, fq * 8), boff = lds_byte(wc * 32 + fr, fq * 8);
;     ...
;     const char* cA = (const char*)g.A + (size_t)cur.pm * tstep; const char* cB = (const char*)g.Bt + (size_t)cur.pn * tstep;
;     PG8_STAGE(PG8_SB(0, 0), cB, voffB); PG8_STAGE(PG8_SA(0, 0), cA, voffA); PG8_STAGE(PG8_SB(0, 1), cB + hstep, voffB); PG8_STAGE(PG8_SA(0, 1), cA + hstep, voffA);
;     if (wr == 1) PG8_BAR;
;     PG8_WAIT_V(4); PG8_BAR;
;     PG8_STAGE(PG8_SB(1, 0), cB + kstep, voffB); PG8_STAGE(PG8_SA(1, 0), cA + kstep, voffA); PG8_STAGE(PG8_SB(1, 1), cB + hstep + kstep, voffB);
;     PG8_WAIT_V(6); PG8_BAR;
.LBB0_426:
	s_and_b32 s3, s3, 3
	s_add_i32 m0, s45, 0x18000
	v_lshl_add_u64 v[8:9], v[8:9], 0, s[24:25]
	s_lshl_b32 s55, s2, 6
	s_lshl_b32 s11, s2, 13
	s_lshl_b32 s58, s3, 5
	s_waitcnt vmcnt(4)
	s_barrier
	global_load_lds_dwordx4 v[8:9], off
	v_lshl_add_u64 v[6:7], v[6:7], 0, s[24:25]
	s_add_i32 m0, s45, 0x1a000
	s_add_i32 s59, s45, 0x8000
	s_add_i32 s60, s45, 0xa000
	global_load_lds_dwordx4 v[6:7], off
	v_lshl_add_u64 v[4:5], v[4:5], 0, s[24:25]
	s_mov_b32 m0, s59
	s_add_u32 s8, s6, 0x40080
	global_load_lds_dwordx4 v[4:5], off
	v_lshl_add_u64 v[2:3], v[2:3], 0, s[24:25]
	s_mov_b32 m0, s60
	s_addc_u32 s9, s7, 0
	global_load_lds_dwordx4 v[2:3], off
	s_add_i32 m0, s45, 0x1c000
	v_lshl_add_u64 v[2:3], s[8:9], 0, v[0:1]
	global_load_lds_dwordx4 v[2:3], off
	v_lshl_add_u64 v[2:3], s[8:9], 0, v[198:199]
	s_add_i32 m0, s45, 0x1e000
	s_ashr_i32 s5, s4, 31
	global_load_lds_dwordx4 v[2:3], off
	v_lshlrev_b32_e32 v3, 2, v207
	v_lshl_or_b32 v2, v207, 6, v240
	v_and_b32_e32 v3, 32, v3
	v_bitop3_b32 v2, v2, s11, v3 bitop3:0xde
	v_cvt_f32_u32_e32 v3, s23
	s_lshl_b32 s68, s2, 2
	s_lshr_b32 s2, s5, 29
	s_add_i32 s2, s4, s2
	v_rcp_iflag_f32_e32 v3, v3
	v_lshl_or_b32 v242, s3, 12, v241
	s_lshl_b32 s3, s3, 11
	s_ashr_i32 s75, s2, 3
	v_mul_f32_e32 v3, 0x4f7ffffe, v3
	v_cvt_u32_f32_e32 v3, v3
	s_and_b32 s2, s2, -8
	s_sub_i32 s76, s4, s2
	s_add_i32 s2, s3, 0
	s_add_i32 s78, s2, s11
	s_sub_i32 s2, 0, s23
	v_mul_lo_u32 v4, s2, v3
	v_mul_hi_u32 v4, v3, v4
	v_add_u32_e32 v243, v3, v4
	v_lshlrev_b32_e32 v3, 14, v219
	v_and_b32_e32 v3, 0xffff8000, v3
	v_lshl_add_u32 v3, v235, 11, v3
	v_and_b32_e32 v4, 1, v219
	v_lshl_or_b32 v3, v4, 6, v3
	v_lshl_add_u32 v200, v236, 1, v3
	v_lshlrev_b32_e32 v3, 14, v237
	v_and_b32_e32 v3, 0xffff8000, v3
	s_waitcnt vmcnt(6)
	v_lshl_add_u32 v3, v238, 11, v3
	v_and_b32_e32 v4, 1, v237
	s_lshr_b32 s61, s55, 4
	v_lshl_or_b32 v3, v4, 6, v3
	s_or_b32 s62, s61, 1
	s_or_b32 s63, s61, 2
	s_or_b32 s64, s61, 3
	s_or_b32 s65, s58, 0x80
	s_or_b32 s69, s68, 1
	s_or_b32 s70, s68, 2
	s_or_b32 s71, s68, 3
	s_waitcnt lgkmcnt(0)
	s_ashr_i32 s74, s48, 31
	s_add_i32 s77, s75, 1
	s_add_i32 s78, s78, 0x20000
	s_mov_b32 s79, 0
	v_mov_b32_e32 v201, v1
	v_lshl_add_u32 v204, v239, 1, v3
	v_mov_b32_e32 v205, v1
	v_add_u32_e32 v244, 0, v2
	s_barrier
	s_waitcnt vmcnt(0)
	s_branch .LBB0_428

; template <class Epi>
; DI void gemm_phase(LAS unsigned char* lds, const Gemm g, const StaticOrder& S, const Epi& E, const int tid) {
;     ...
;         const bool has_next = S.next(ui + 1, nxt);
;         const char* nA = has_next ? (const char*)g.A + (size_t)nxt.pm * tstep : cA; const char* nB = has_next ? (const char*)g.Bt + (size_t)nxt.pn * tstep : cB;
;         for (int t = 0; t < nt; t += 2) {
;             const bool last = (t == nt - 2);
;             const char* a1 = cA + (size_t)(t + 1) * kstep;
;             const char* a2 = last ? nA : cA + (size_t)(t + 2) * kstep; const char* b2 = last ? nB : cB + (size_t)(t + 2) * kstep;
;             const char* a3 = a2 + kstep; const char* b3 = b2 + kstep;
;     ...
; #pragma unroll
;         for (int a = 0; a < 2; ++a)
; #pragma unroll
;             for (int b = 0; b < 2; ++b)
; #pragma unroll
;                 for (int m = 0; m < 4; ++m)
; #pragma unroll
;                     for (int n = 0; n < 2; ++n) acc[a][b][m][n] = (f32x4){0.f, 0.f, 0.f, 0.f};
;         cur = nxt; cA = nA; cB = nB; ++ui;
.LBB0_434:
	s_ashr_i32 s31, s30, 31
	s_lshl_b64 s[2:3], s[30:31], 19
	v_readlane_b32 s12, v254, 63
	v_mov_b64_e32 v[2:3], s[4:5]
	v_readlane_b32 s13, v255, 0
	s_add_u32 s34, s12, s2
	v_cmp_lt_i64_e32 vcc, s[16:17], v[2:3]
	s_addc_u32 s35, s13, s3
	s_and_b64 s[2:3], vcc, exec
	s_cselect_b32 s2, s35, s1
	s_cselect_b32 s3, s34, s0
	s_ashr_i32 s9, s8, 31
	s_lshl_b64 s[12:13], s[8:9], 19
	s_add_u32 s40, s21, s12
	s_addc_u32 s41, s51, s13
	s_and_b64 s[12:13], vcc, exec
	s_cselect_b32 s9, s41, s7
	s_cselect_b32 s11, s40, s6
	s_add_u32 s0, s0, 0x40080
	s_addc_u32 s1, s1, 0
	s_add_u32 s12, s6, 0x100
	v_mov_b32_e32 v2, 0
	s_addc_u32 s13, s7, 0
	s_mov_b32 s14, -2
	v_mov_b32_e32 v3, v2
	v_mov_b32_e32 v4, v2
	v_mov_b32_e32 v5, v2
	v_mov_b32_e32 v6, v2
	v_mov_b32_e32 v7, v2
	v_mov_b32_e32 v8, v2
	v_mov_b32_e32 v9, v2
	v_mov_b32_e32 v18, v2
	v_mov_b32_e32 v19, v2
	v_mov_b32_e32 v20, v2
	v_mov_b32_e32 v21, v2
	v_mov_b32_e32 v22, v2
	v_mov_b32_e32 v23, v2
	v_mov_b32_e32 v24, v2
	v_mov_b32_e32 v25, v2
	v_mov_b32_e32 v34, v2
	v_mov_b32_e32 v35, v2
	v_mov_b32_e32 v36, v2
	v_mov_b32_e32 v37, v2
	v_mov_b32_e32 v38, v2
	v_mov_b32_e32 v39, v2
	v_mov_b32_e32 v40, v2
	v_mov_b32_e32 v41, v2
	v_mov_b32_e32 v50, v2
	v_mov_b32_e32 v51, v2
	v_mov_b32_e32 v52, v2
	v_mov_b32_e32 v53, v2
	v_mov_b32_e32 v54, v2
	v_mov_b32_e32 v55, v2
	v_mov_b32_e32 v56, v2
	v_mov_b32_e32 v57, v2
	v_mov_b32_e32 v10, v2
	v_mov_b32_e32 v11, v2
	v_mov_b32_e32 v12, v2
	v_mov_b32_e32 v13, v2
	v_mov_b32_e32 v14, v2
	v_mov_b32_e32 v15, v2
	v_mov_b32_e32 v16, v2
	v_mov_b32_e32 v17, v2
	v_mov_b32_e32 v26, v2
	v_mov_b32_e32 v27, v2
	v_mov_b32_e32 v28, v2
	v_mov_b32_e32 v29, v2
	v_mov_b32_e32 v30, v2
	v_mov_b32_e32 v31, v2
	v_mov_b32_e32 v32, v2
	v_mov_b32_e32 v33, v2
	v_mov_b32_e32 v42, v2
	v_mov_b32_e32 v43, v2
	v_mov_b32_e32 v44, v2
	v_mov_b32_e32 v45, v2
	v_mov_b32_e32 v46, v2
	v_mov_b32_e32 v47, v2
	v_mov_b32_e32 v48, v2
	v_mov_b32_e32 v49, v2
	v_mov_b32_e32 v58, v2
	v_mov_b32_e32 v59, v2
	v_mov_b32_e32 v60, v2
	v_mov_b32_e32 v61, v2
	v_mov_b32_e32 v62, v2
	v_mov_b32_e32 v63, v2
	v_mov_b32_e32 v64, v2
	v_mov_b32_e32 v65, v2
	v_mov_b32_e32 v66, v2
	v_mov_b32_e32 v67, v2
	v_mov_b32_e32 v68, v2
	v_mov_b32_e32 v69, v2
	v_mov_b32_e32 v70, v2
	v_mov_b32_e32 v71, v2
	v_mov_b32_e32 v72, v2
	v_mov_b32_e32 v73, v2
	v_mov_b32_e32 v82, v2
	v_mov_b32_e32 v83, v2
	v_mov_b32_e32 v84, v2
	v_mov_b32_e32 v85, v2
	v_mov_b32_e32 v86, v2
	v_mov_b32_e32 v87, v2
	v_mov_b32_e32 v88, v2
	v_mov_b32_e32 v89, v2
	v_mov_b32_e32 v98, v2
	v_mov_b32_e32 v99, v2
	v_mov_b32_e32 v100, v2
	v_mov_b32_e32 v101, v2
	v_mov_b32_e32 v102, v2
	v_mov_b32_e32 v103, v2
	v_mov_b32_e32 v104, v2
	v_mov_b32_e32 v105, v2
	v_mov_b32_e32 v114, v2
	v_mov_b32_e32 v115, v2
	v_mov_b32_e32 v116, v2
	v_mov_b32_e32 v117, v2
	v_mov_b32_e32 v118, v2
	v_mov_b32_e32 v119, v2
	v_mov_b32_e32 v120, v2
	v_mov_b32_e32 v121, v2
	v_mov_b32_e32 v74, v2
	v_mov_b32_e32 v75, v2
	v_mov_b32_e32 v76, v2
	v_mov_b32_e32 v77, v2
	v_mov_b32_e32 v78, v2
	v_mov_b32_e32 v79, v2
	v_mov_b32_e32 v80, v2
	v_mov_b32_e32 v81, v2
	v_mov_b32_e32 v90, v2
	v_mov_b32_e32 v91, v2
	v_mov_b32_e32 v92, v2
	v_mov_b32_e32 v93, v2
	v_mov_b32_e32 v94, v2
	v_mov_b32_e32 v95, v2
	v_mov_b32_e32 v96, v2
	v_mov_b32_e32 v97, v2
	v_mov_b32_e32 v106, v2
	v_mov_b32_e32 v107, v2
	v_mov_b32_e32 v108, v2
	v_mov_b32_e32 v109, v2
	v_mov_b32_e32 v110, v2
	v_mov_b32_e32 v111, v2
	v_mov_b32_e32 v112, v2
	v_mov_b32_e32 v113, v2
	v_mov_b32_e32 v122, v2
	v_mov_b32_e32 v123, v2
	v_mov_b32_e32 v124, v2
	v_mov_b32_e32 v125, v2
	v_mov_b32_e32 v126, v2
	v_mov_b32_e32 v127, v2
	v_mov_b32_e32 v128, v2
	v_mov_b32_e32 v129, v2
